# spatial gating: masked bf16 weight tile kept in LDS across the sg units of a workgroup (same group g), restaged only by the first
# speedup vs baseline: 1.0174x; 1.0071x over previous
; __device__ __forceinline__ void sg_unit(LAS unsigned char* lds, const bf16_t* P0, bf16_t* MIX, const float* lng, const float* lnb, const float* wsp, const float* bsp, int b, int nch, int g) {
;     ...
;     __syncthreads();
;     {
;         const int s = tid >> 2, part = tid & 3;
;         const bf16_t* vp = P0 + (rowbase + s) * AB_IN + 512 + 128 * g + 32 * part;
;         float x[32]; float sum = 0.f;
; #pragma unroll
;         for (int j = 0; j < 4; ++j) { const u32x4 wv = *(const u32x4*)(vp + 8 * j);
;             x[8 * j + 0] = bflo(wv.x); x[8 * j + 1] = bfhi(wv.x); x[8 * j + 2] = bflo(wv.y); x[8 * j + 3] = bfhi(wv.y);
;             x[8 * j + 4] = bflo(wv.z); x[8 * j + 5] = bfhi(wv.z); x[8 * j + 6] = bflo(wv.w); x[8 * j + 7] = bfhi(wv.w); }
; #pragma unroll
;         for (int j = 0; j < 32; ++j) sum += x[j];
;         sum += __shfl_xor(sum, 1); sum += __shfl_xor(sum, 2);
;         const float mean = sum * (1.f / 128.f); float q = 0.f;
; #pragma unroll
;         for (int j = 0; j < 32; ++j) { x[j] -= mean; q += x[j] * x[j]; }
;         q += __shfl_xor(q, 1); q += __shfl_xor(q, 2);
;         const float rstd = __builtin_amdgcn_rsqf(q * (1.f / 128.f) + LN_EPS);
.LBB0_290:
	s_cmpk_gt_i32 s33, 0x7ff
	s_mov_b64 s[0:1], -1
	s_cbranch_scc0 .LBB0_294
	s_lshl_b32 s1, s33, 5
	s_and_b32 s5, s1, 0x7fffff80
	s_add_i32 s5, s5, 0xffff0000
	v_add_u32_e32 v0, s5, v81
	s_and_b32 s0, s33, 3
	v_mul_lo_u32 v72, v0, s3
	v_lshl_add_u64 v[0:1], s[26:27], 0, v[72:73]
	s_lshl_b32 s22, s0, 8
	v_lshl_add_u64 v[0:1], v[0:1], 0, s[22:23]
	v_mov_b32_e32 v91, v73
	s_waitcnt vmcnt(7)
	v_lshl_add_u64 v[12:13], v[0:1], 0, v[90:91]
	s_barrier
	global_load_dwordx4 v[0:3], v[12:13], off offset:1072
	global_load_dwordx4 v[4:7], v[12:13], off offset:1056
	global_load_dwordx4 v[8:11], v[12:13], off offset:1040
	s_nop 0
	global_load_dwordx4 v[12:15], v[12:13], off offset:1024
	v_cmp_lt_i32_e32 vcc, v113, v114
	s_lshl_b32 s22, s0, 9
	s_lshl_b32 s4, s0, 7
	s_lshl_b32 s0, s0, 14
	v_add_lshl_u32 v72, s0, v83, 2
	v_readlane_b32 s0, v254, 18
	v_readlane_b32 s1, v254, 19
	s_waitcnt vmcnt(2)
	v_lshlrev_b32_e32 v24, 16, v4
	s_waitcnt vmcnt(1)
	v_lshlrev_b32_e32 v32, 16, v8
	s_waitcnt vmcnt(0)
	v_lshlrev_b32_e32 v40, 16, v12
	v_and_b32_e32 v39, 0xffff0000, v12
	v_lshlrev_b32_e32 v36, 16, v14
	v_and_b32_e32 v35, 0xffff0000, v14
	v_lshlrev_b32_e32 v34, 16, v15
	v_and_b32_e32 v33, 0xffff0000, v15
	v_lshlrev_b32_e32 v15, 16, v0
	v_and_b32_e32 v14, 0xffff0000, v0
	v_add_f32_e32 v0, 0, v40
	v_lshlrev_b32_e32 v38, 16, v13
	v_add_f32_e32 v0, v0, v39
	v_and_b32_e32 v37, 0xffff0000, v13
	v_add_f32_e32 v0, v0, v38
	v_add_f32_e32 v0, v0, v37
	v_add_f32_e32 v0, v0, v36
	v_add_f32_e32 v0, v0, v35
	v_add_f32_e32 v0, v0, v34
	v_add_f32_e32 v0, v0, v33
	v_and_b32_e32 v31, 0xffff0000, v8
	v_add_f32_e32 v0, v0, v32
	v_lshlrev_b32_e32 v30, 16, v9
	v_add_f32_e32 v0, v0, v31
	v_and_b32_e32 v29, 0xffff0000, v9
	v_add_f32_e32 v0, v0, v30
	v_lshlrev_b32_e32 v28, 16, v10
	v_add_f32_e32 v0, v0, v29
	v_and_b32_e32 v27, 0xffff0000, v10
	v_add_f32_e32 v0, v0, v28
	v_lshlrev_b32_e32 v26, 16, v11
	v_add_f32_e32 v0, v0, v27
	v_and_b32_e32 v25, 0xffff0000, v11
	v_add_f32_e32 v0, v0, v26
	v_add_f32_e32 v0, v0, v25
	v_and_b32_e32 v22, 0xffff0000, v4
	v_add_f32_e32 v0, v0, v24
	v_lshlrev_b32_e32 v21, 16, v5
	v_add_f32_e32 v0, v0, v22
	v_and_b32_e32 v20, 0xffff0000, v5
	v_add_f32_e32 v0, v0, v21
	v_lshlrev_b32_e32 v19, 16, v6
	v_add_f32_e32 v0, v0, v20
	v_and_b32_e32 v18, 0xffff0000, v6
	v_add_f32_e32 v0, v0, v19
	v_lshlrev_b32_e32 v17, 16, v7
	v_add_f32_e32 v0, v0, v18
	v_and_b32_e32 v16, 0xffff0000, v7
	v_add_f32_e32 v0, v0, v17
	v_add_f32_e32 v0, v0, v16
	v_add_f32_e32 v0, v0, v15
	v_lshlrev_b32_e32 v13, 16, v1
	v_add_f32_e32 v0, v0, v14
	v_and_b32_e32 v12, 0xffff0000, v1
	v_add_f32_e32 v0, v0, v13
	v_lshlrev_b32_e32 v11, 16, v2
	v_add_f32_e32 v0, v0, v12
	v_and_b32_e32 v10, 0xffff0000, v2
	v_add_f32_e32 v0, v0, v11
	v_add_f32_e32 v2, v0, v10
	v_cndmask_b32_e32 v0, v112, v113, vcc
	v_cmp_lt_i32_e32 vcc, v115, v114
	v_lshlrev_b32_e32 v6, 2, v0
	v_lshlrev_b32_e32 v1, 16, v3
	v_cndmask_b32_e32 v0, v112, v115, vcc
	v_lshlrev_b32_e32 v7, 2, v0
	v_and_b32_e32 v0, 0xffff0000, v3
	v_add_f32_e32 v2, v2, v1
	v_add_f32_e32 v2, v2, v0
	ds_bpermute_b32 v3, v6, v2
	s_waitcnt lgkmcnt(0)
	v_add_f32_e32 v2, v2, v3
	ds_bpermute_b32 v3, v7, v2
	s_waitcnt lgkmcnt(0)
	v_add_f32_e32 v3, v2, v3
	v_fmac_f32_e32 v39, 0xbc000000, v3
	v_fmac_f32_e32 v40, 0xbc000000, v3
	v_mul_f32_e32 v8, v39, v39
	v_fmac_f32_e32 v8, v40, v40
	v_fmac_f32_e32 v38, 0xbc000000, v3
	v_fmac_f32_e32 v8, v38, v38
	v_fmac_f32_e32 v37, 0xbc000000, v3
	v_fmac_f32_e32 v8, v37, v37
	v_fmac_f32_e32 v36, 0xbc000000, v3
	v_fmac_f32_e32 v8, v36, v36
	v_fmac_f32_e32 v35, 0xbc000000, v3
	v_fmac_f32_e32 v8, v35, v35
	v_fmac_f32_e32 v34, 0xbc000000, v3
	v_fmac_f32_e32 v8, v34, v34
	v_fmac_f32_e32 v33, 0xbc000000, v3
	v_fmac_f32_e32 v8, v33, v33
	v_fmac_f32_e32 v32, 0xbc000000, v3
	v_fmac_f32_e32 v8, v32, v32
	v_fmac_f32_e32 v31, 0xbc000000, v3
	v_fmac_f32_e32 v8, v31, v31
	v_fmac_f32_e32 v30, 0xbc000000, v3
	v_fmac_f32_e32 v8, v30, v30
	v_fmac_f32_e32 v29, 0xbc000000, v3
	v_fmac_f32_e32 v8, v29, v29
	v_fmac_f32_e32 v28, 0xbc000000, v3
	v_fmac_f32_e32 v8, v28, v28
	v_fmac_f32_e32 v27, 0xbc000000, v3
	v_fmac_f32_e32 v8, v27, v27
	v_fmac_f32_e32 v26, 0xbc000000, v3
	v_fmac_f32_e32 v8, v26, v26
	v_fmac_f32_e32 v25, 0xbc000000, v3
	v_fmac_f32_e32 v8, v25, v25
	v_fmac_f32_e32 v24, 0xbc000000, v3
	v_fmac_f32_e32 v8, v24, v24
	v_fmac_f32_e32 v22, 0xbc000000, v3
	v_fmac_f32_e32 v8, v22, v22
	v_fmac_f32_e32 v21, 0xbc000000, v3
	v_fmac_f32_e32 v8, v21, v21
	v_fmac_f32_e32 v20, 0xbc000000, v3
	v_fmac_f32_e32 v8, v20, v20
	v_fmac_f32_e32 v19, 0xbc000000, v3
	v_fmac_f32_e32 v8, v19, v19
	v_fmac_f32_e32 v18, 0xbc000000, v3
	v_fmac_f32_e32 v8, v18, v18
	v_fmac_f32_e32 v17, 0xbc000000, v3
	v_fmac_f32_e32 v8, v17, v17
	v_fmac_f32_e32 v16, 0xbc000000, v3
	v_fmac_f32_e32 v8, v16, v16
	v_fmac_f32_e32 v15, 0xbc000000, v3
	v_fmac_f32_e32 v8, v15, v15
	v_fmac_f32_e32 v14, 0xbc000000, v3
	v_fmac_f32_e32 v8, v14, v14
	v_fmac_f32_e32 v13, 0xbc000000, v3
	v_fmac_f32_e32 v8, v13, v13
	v_fmac_f32_e32 v12, 0xbc000000, v3
	v_mul_f32_e32 v2, 0x3c000000, v3
	v_fmac_f32_e32 v8, v12, v12
	v_fmac_f32_e32 v11, 0xbc000000, v3
	v_fmac_f32_e32 v8, v11, v11
	v_fmac_f32_e32 v10, 0xbc000000, v3
	v_pk_add_f32 v[4:5], v[0:1], v[2:3] op_sel_hi:[1,0] neg_lo:[0,1] neg_hi:[0,1]
	v_fmac_f32_e32 v8, v10, v10
	v_pk_mul_f32 v[0:1], v[4:5], v[4:5]
	s_nop 0
	v_add_f32_e32 v1, v1, v8
	v_add_f32_e32 v0, v0, v1
	ds_bpermute_b32 v1, v6, v0
	v_lshl_add_u64 v[8:9], v[74:75], 0, s[22:23]
	s_waitcnt lgkmcnt(0)
	v_add_f32_e32 v0, v0, v1
	ds_bpermute_b32 v1, v7, v0
	v_lshl_add_u64 v[6:7], v[76:77], 0, s[22:23]
	s_waitcnt lgkmcnt(0)
; #define LAS __attribute__((address_space(3)))
; __device__ __forceinline__ unsigned pk2(float lo, float hi) { unsigned r; asm("v_cvt_pk_bf16_f32 %0, %1, %2" : "=v"(r) : "v"(lo), "v"(hi)); return r; }
; __device__ __forceinline__ void sg_unit(LAS unsigned char* lds, const bf16_t* P0, bf16_t* MIX, const float* lng, const float* lnb, const float* wsp, const float* bsp, int b, int nch, int g) {
;     ...
;         const float rstd = __builtin_amdgcn_rsqf(q * (1.f / 128.f) + LN_EPS);
;         const float* gp = lng + 128 * g + 32 * part; const float* bp = lnb + 128 * g + 32 * part;
; #pragma unroll
;         for (int j = 0; j < 4; ++j) { float y[8];
; #pragma unroll
;             for (int e = 0; e < 8; ++e) y[e] = x[8 * j + e] * rstd * gp[8 * j + e] + bp[8 * j + e];
;             *(LAS u32x4*)(vnl + s * 136 + 32 * part + 8 * j) = (u32x4){pk2(y[0], y[1]), pk2(y[2], y[3]), pk2(y[4], y[5]), pk2(y[6], y[7])}; }
	v_add_f32_e32 v0, v0, v1
	v_fmamk_f32 v0, v0, 0x3c000000, v106
	v_rsq_f32_e32 v23, v0
	s_nop 0
	v_mul_f32_e32 v52, v40, v23
	global_load_dwordx4 v[0:3], v[8:9], off offset:16
	global_load_dwordx4 v[40:43], v[8:9], off
	global_load_dwordx4 v[44:47], v[6:7], off offset:16
	global_load_dwordx4 v[48:51], v[6:7], off
	v_mul_f32_e32 v36, v36, v23
	v_mul_f32_e32 v39, v39, v23
	v_mul_f32_e32 v38, v38, v23
	v_mul_f32_e32 v37, v37, v23
	v_mul_f32_e32 v28, v28, v23
	v_mul_f32_e32 v31, v31, v23
	v_mul_f32_e32 v30, v30, v23
	v_mul_f32_e32 v29, v29, v23
	v_mul_f32_e32 v19, v19, v23
	v_mul_f32_e32 v22, v22, v23
	v_mul_f32_e32 v21, v21, v23
	v_mul_f32_e32 v20, v20, v23
	v_mul_f32_e32 v11, v11, v23
	v_mul_f32_e32 v15, v15, v23
	v_mul_f32_e32 v14, v14, v23
	v_mul_f32_e32 v13, v13, v23
	v_mul_f32_e32 v12, v12, v23
	s_waitcnt vmcnt(1)
	v_fma_f32 v36, v0, v36, v44
	v_mul_f32_e32 v0, v35, v23
	v_fma_f32 v35, v1, v0, v45
	v_mul_f32_e32 v0, v34, v23
	v_fma_f32 v34, v2, v0, v46
	v_mul_f32_e32 v0, v33, v23
	s_waitcnt vmcnt(0)
	v_fma_f32 v40, v40, v52, v48
	v_fma_f32 v39, v41, v39, v49
	v_fma_f32 v38, v42, v38, v50
	v_fmac_f32_e32 v51, v43, v37
	v_fmac_f32_e32 v47, v3, v0
	v_cvt_pk_bf16_f32 v0, v40, v39
	v_cvt_pk_bf16_f32 v1, v38, v51
	v_cvt_pk_bf16_f32 v2, v36, v35
	v_cvt_pk_bf16_f32 v3, v34, v47
	ds_write_b128 v107, v[0:3]
	v_mul_f32_e32 v44, v32, v23
	global_load_dwordx4 v[0:3], v[8:9], off offset:48
	global_load_dwordx4 v[32:35], v[8:9], off offset:32
	global_load_dwordx4 v[36:39], v[6:7], off offset:48
	global_load_dwordx4 v[40:43], v[6:7], off offset:32
	s_waitcnt vmcnt(1)
	v_fma_f32 v28, v0, v28, v36
	v_mul_f32_e32 v0, v27, v23
	v_fma_f32 v27, v1, v0, v37
	v_mul_f32_e32 v0, v26, v23
	v_fma_f32 v26, v2, v0, v38
	v_mul_f32_e32 v0, v25, v23
	s_waitcnt vmcnt(0)
	v_fma_f32 v32, v32, v44, v40
	v_fma_f32 v31, v33, v31, v41
	v_fma_f32 v30, v34, v30, v42
	v_fmac_f32_e32 v43, v35, v29
	v_fmac_f32_e32 v39, v3, v0
	v_cvt_pk_bf16_f32 v0, v32, v31
	v_cvt_pk_bf16_f32 v1, v30, v43
	v_cvt_pk_bf16_f32 v2, v28, v27
	v_cvt_pk_bf16_f32 v3, v26, v39
	ds_write_b128 v107, v[0:3] offset:16
	v_mul_f32_e32 v36, v24, v23
	global_load_dwordx4 v[0:3], v[8:9], off offset:80
	global_load_dwordx4 v[24:27], v[8:9], off offset:64
	global_load_dwordx4 v[28:31], v[6:7], off offset:80
	global_load_dwordx4 v[32:35], v[6:7], off offset:64
	s_waitcnt vmcnt(1)
	v_fma_f32 v19, v0, v19, v28
	v_mul_f32_e32 v0, v18, v23
	v_fma_f32 v18, v1, v0, v29
	v_mul_f32_e32 v0, v17, v23
	v_fma_f32 v17, v2, v0, v30
	v_mul_f32_e32 v0, v16, v23
	s_waitcnt vmcnt(0)
	v_fma_f32 v24, v24, v36, v32
	v_fma_f32 v22, v25, v22, v33
	v_fma_f32 v21, v26, v21, v34
	v_fmac_f32_e32 v35, v27, v20
	v_fmac_f32_e32 v31, v3, v0
	v_cvt_pk_bf16_f32 v0, v24, v22
	v_cvt_pk_bf16_f32 v1, v21, v35
	v_cvt_pk_bf16_f32 v2, v19, v18
	v_cvt_pk_bf16_f32 v3, v17, v31
	ds_write_b128 v107, v[0:3] offset:32
	global_load_dwordx4 v[0:3], v[8:9], off offset:112
	global_load_dwordx4 v[16:19], v[8:9], off offset:96
	global_load_dwordx4 v[24:27], v[6:7], off offset:112
	s_nop 0
	global_load_dwordx4 v[6:9], v[6:7], off offset:96
	v_mov_b32_e32 v32, v105
	v_mov_b32_e32 v33, v104
	v_mov_b32_e32 v34, v103
	s_waitcnt vmcnt(1)
	v_fma_f32 v11, v11, v0, v24
	v_mul_f32_e32 v0, v10, v23
	v_fma_f32 v10, v0, v1, v25
	v_mul_f32_e32 v0, v5, v23
	v_fma_f32 v5, v0, v2, v26
	v_mul_f32_e32 v0, v4, v23
	s_waitcnt vmcnt(0)
	v_fma_f32 v6, v16, v15, v6
	v_fma_f32 v7, v17, v14, v7
	v_fma_f32 v8, v18, v13, v8
	v_fmac_f32_e32 v9, v12, v19
	v_fmac_f32_e32 v27, v0, v3
	v_cvt_pk_bf16_f32 v0, v6, v7
	v_cvt_pk_bf16_f32 v1, v8, v9
	v_cvt_pk_bf16_f32 v2, v11, v10
	v_cvt_pk_bf16_f32 v3, v5, v27
	ds_write_b128 v107, v[0:3] offset:48
	v_readlane_b32 s98, v254, 8
	s_nop 0
	s_and_b32 s99, s98, 3
	s_sub_i32 s98, s33, s98
	s_cmp_lg_u32 s99, 0
	s_cbranch_scc1 .Lsg_stage_w
	s_cmpk_gt_i32 s98, 0x7ff
	s_cbranch_scc1 .Lsg_skip_w
; #define LAS __attribute__((address_space(3)))
; __device__ __forceinline__ unsigned pk2(float lo, float hi) { unsigned r; asm("v_cvt_pk_bf16_f32 %0, %1, %2" : "=v"(r) : "v"(lo), "v"(hi)); return r; }
; __device__ __forceinline__ void sg_unit(LAS unsigned char* lds, const bf16_t* P0, bf16_t* MIX, const float* lng, const float* lnb, const float* wsp, const float* bsp, int b, int nch, int g) {
;     ...
;         const int t = tid >> 2, s0 = 32 * part; const float* wp = wsp + ((size_t)g * 128 + t) * 128 + s0;
; #pragma unroll
;         for (int j = 0; j < 4; ++j) { const f32x4 a0 = *(const f32x4*)(wp + 8 * j), a1 = *(const f32x4*)(wp + 8 * j + 4); const int sb = s0 + 8 * j;
;             u32x4 o; o.x = pk2(sb + 0 <= t ? a0.x : 0.f, sb + 1 <= t ? a0.y : 0.f); o.y = pk2(sb + 2 <= t ? a0.z : 0.f, sb + 3 <= t ? a0.w : 0.f);
;             o.z = pk2(sb + 4 <= t ? a1.x : 0.f, sb + 5 <= t ? a1.y : 0.f); o.w = pk2(sb + 6 <= t ? a1.z : 0.f, sb + 7 <= t ? a1.w : 0.f);
;             *(LAS u32x4*)(Wl + t * 136 + sb) = o; }
;     }
;     __syncthreads();
;     f32x4 acc[8];
; #pragma unroll
;     for (int mi = 0; mi < 8; ++mi) acc[mi] = (f32x4){0.f, 0.f, 0.f, 0.f};
.Lsg_stage_w:
	v_lshl_add_u64 v[4:5], v[78:79], 0, v[72:73]
	global_load_dwordx4 v[0:3], v[4:5], off offset:16
	global_load_dwordx4 v[6:9], v[4:5], off
	s_waitcnt vmcnt(0)
	v_cndmask_b32_e64 v6, v6, 0, s[0:1]
	v_readlane_b32 s0, v254, 16
	v_readlane_b32 s1, v254, 17
	s_nop 1
	v_cndmask_b32_e64 v7, 0, v7, s[0:1]
	v_readlane_b32 s0, v254, 14
	v_readlane_b32 s1, v254, 15
	v_cvt_pk_bf16_f32 v6, v6, v7
	s_nop 1
	v_cndmask_b32_e64 v7, v8, 0, s[0:1]
	v_readlane_b32 s0, v254, 10
	v_readlane_b32 s1, v254, 11
	s_nop 1
	v_cndmask_b32_e64 v8, v9, 0, s[0:1]
	v_readlane_b32 s0, v254, 12
	v_readlane_b32 s1, v254, 13
	v_cvt_pk_bf16_f32 v7, v7, v8
	s_nop 1
	v_cndmask_b32_e64 v0, v0, 0, s[0:1]
	v_readlane_b32 s0, v254, 22
	v_readlane_b32 s1, v254, 23
	s_nop 1
	v_cndmask_b32_e64 v1, v1, 0, s[0:1]
	v_readlane_b32 s0, v254, 24
	v_readlane_b32 s1, v254, 25
	v_cvt_pk_bf16_f32 v8, v0, v1
	s_nop 1
	v_cndmask_b32_e64 v0, v2, 0, s[0:1]
	v_readlane_b32 s0, v254, 26
	v_readlane_b32 s1, v254, 27
	s_nop 1
	v_cndmask_b32_e64 v1, v3, 0, s[0:1]
	v_cvt_pk_bf16_f32 v9, v0, v1
	ds_write_b128 v85, v[6:9] offset:34816
	global_load_dwordx4 v[0:3], v[4:5], off offset:48
	global_load_dwordx4 v[6:9], v[4:5], off offset:32
	v_readlane_b32 s0, v254, 28
	v_readlane_b32 s1, v254, 29
	s_waitcnt vmcnt(0)
	s_nop 0
	v_cndmask_b32_e64 v6, v6, 0, s[0:1]
	v_readlane_b32 s0, v254, 30
	v_readlane_b32 s1, v254, 31
	s_nop 1
	v_cndmask_b32_e64 v7, 0, v7, s[0:1]
	v_readlane_b32 s0, v254, 32
	v_readlane_b32 s1, v254, 33
	v_cvt_pk_bf16_f32 v6, v6, v7
	s_nop 1
	v_cndmask_b32_e64 v7, v8, 0, s[0:1]
	v_readlane_b32 s0, v254, 34
	v_readlane_b32 s1, v254, 35
	s_nop 1
	v_cndmask_b32_e64 v8, v9, 0, s[0:1]
	v_readlane_b32 s0, v254, 36
	v_readlane_b32 s1, v254, 37
	v_cvt_pk_bf16_f32 v7, v7, v8
	s_nop 1
	v_cndmask_b32_e64 v0, v0, 0, s[0:1]
	v_readlane_b32 s0, v254, 38
	v_readlane_b32 s1, v254, 39
	s_nop 1
	v_cndmask_b32_e64 v1, v1, 0, s[0:1]
	v_readlane_b32 s0, v254, 40
	v_readlane_b32 s1, v254, 41
	v_cvt_pk_bf16_f32 v8, v0, v1
	s_nop 1
	v_cndmask_b32_e64 v0, v2, 0, s[0:1]
	v_readlane_b32 s0, v254, 42
	v_readlane_b32 s1, v254, 43
	s_nop 1
	v_cndmask_b32_e64 v1, v3, 0, s[0:1]
	v_cvt_pk_bf16_f32 v9, v0, v1
	ds_write_b128 v85, v[6:9] offset:34832
	global_load_dwordx4 v[0:3], v[4:5], off offset:80
	global_load_dwordx4 v[6:9], v[4:5], off offset:64
	v_readlane_b32 s0, v254, 44
	v_readlane_b32 s1, v254, 45
	s_waitcnt vmcnt(0)
	s_nop 0
	v_cndmask_b32_e64 v6, v6, 0, s[0:1]
	v_readlane_b32 s0, v254, 46
	v_readlane_b32 s1, v254, 47
	s_nop 1
	v_cndmask_b32_e64 v7, 0, v7, s[0:1]
	v_readlane_b32 s0, v254, 48
	v_readlane_b32 s1, v254, 49
	v_cvt_pk_bf16_f32 v6, v6, v7
	s_nop 1
	v_cndmask_b32_e64 v7, v8, 0, s[0:1]
	v_readlane_b32 s0, v254, 50
	v_readlane_b32 s1, v254, 51
	s_nop 1
	v_cndmask_b32_e64 v8, v9, 0, s[0:1]
	v_readlane_b32 s0, v254, 52
	v_readlane_b32 s1, v254, 53
	v_cvt_pk_bf16_f32 v7, v7, v8
	s_nop 1
	v_cndmask_b32_e64 v0, v0, 0, s[0:1]
	v_readlane_b32 s0, v254, 54
	v_readlane_b32 s1, v254, 55
	s_nop 1
	v_cndmask_b32_e64 v1, v1, 0, s[0:1]
	v_readlane_b32 s0, v254, 56
	v_readlane_b32 s1, v254, 57
	v_cvt_pk_bf16_f32 v8, v0, v1
	s_nop 1
	v_cndmask_b32_e64 v0, v2, 0, s[0:1]
	v_readlane_b32 s0, v254, 58
	v_readlane_b32 s1, v254, 59
	s_nop 1
	v_cndmask_b32_e64 v1, v3, 0, s[0:1]
	v_cvt_pk_bf16_f32 v9, v0, v1
	ds_write_b128 v85, v[6:9] offset:34848
	global_load_dwordx4 v[0:3], v[4:5], off offset:112
	s_nop 0
	global_load_dwordx4 v[4:7], v[4:5], off offset:96
	v_readlane_b32 s0, v254, 60
	v_readlane_b32 s1, v254, 61
	s_waitcnt vmcnt(1)
	v_cndmask_b32_e64 v0, v0, 0, s[30:31]
	s_waitcnt vmcnt(0)
	v_cndmask_b32_e64 v4, v4, 0, s[0:1]
	v_readlane_b32 s0, v254, 62
	v_readlane_b32 s1, v254, 63
	v_cndmask_b32_e64 v1, v1, 0, s[34:35]
	s_nop 0
	v_cndmask_b32_e64 v5, 0, v5, s[0:1]
	v_cvt_pk_bf16_f32 v4, v4, v5
	v_cndmask_b32_e64 v5, v6, 0, s[64:65]
	v_cndmask_b32_e64 v6, v7, 0, s[28:29]
	v_cvt_pk_bf16_f32 v5, v5, v6
	v_cvt_pk_bf16_f32 v6, v0, v1
	v_cndmask_b32_e64 v0, v2, 0, s[38:39]
	v_cndmask_b32_e64 v1, v3, 0, s[68:69]
	v_cvt_pk_bf16_f32 v7, v0, v1
	v_mov_b32_e32 v0, 0
	ds_write_b128 v85, v[4:7] offset:34864
.Lsg_skip_w:
	v_mov_b32_e32 v0, 0
	s_mov_b64 s[0:1], 0
	v_mov_b32_e32 v1, v0
	v_mov_b32_e32 v2, v0
	v_mov_b32_e32 v3, v0
	v_mov_b32_e32 v4, v0
	v_mov_b32_e32 v5, v0
	v_mov_b32_e32 v6, v0
	v_mov_b32_e32 v7, v0
	v_mov_b32_e32 v8, v0
	v_mov_b32_e32 v9, v0
	v_mov_b32_e32 v10, v0
	v_mov_b32_e32 v11, v0
	v_mov_b32_e32 v12, v0
	v_mov_b32_e32 v13, v0
	v_mov_b32_e32 v14, v0
	v_mov_b32_e32 v15, v0
	v_mov_b32_e32 v16, v0
	v_mov_b32_e32 v17, v0
	v_mov_b32_e32 v18, v0
	v_mov_b32_e32 v19, v0
	v_mov_b32_e32 v20, v0
	v_mov_b32_e32 v21, v0
	v_mov_b32_e32 v22, v0
	v_mov_b32_e32 v23, v0
	v_mov_b32_e32 v24, v0
	v_mov_b32_e32 v25, v0
	v_mov_b32_e32 v26, v0
	v_mov_b32_e32 v27, v0
	v_mov_b32_e32 v28, v0
	v_mov_b32_e32 v29, v0
	v_mov_b32_e32 v30, v0
	v_mov_b32_e32 v31, v0
	s_waitcnt lgkmcnt(0)
	s_barrier
